# down-proj epilogue rewritten by hand: all residual loads up front as 16 dwordx4 (column-block pairs, redistributed with v_permlane16_swap) instead of 32 dwordx2 in two batches, counted vmcnt waits, sc
# speedup vs baseline: 1.0152x; 1.0054x over previous
; #define LAS __attribute__((address_space(3)))
;     DI void operator()(const AccT& acc, const Unit& u, int wr, int wc, int fr, int fq, LAS unsigned char*) const {
;         const int col0 = u.pn * 256 + wc * 32 + 4 * fq;
; #pragma unroll
;         for (int ai = 0; ai < 2; ++ai) {
;             u32x2 xb[4][2][2];
; #pragma unroll
;             for (int m = 0; m < 4; ++m) {
;                 const int row = u.pm * 256 + ai * 128 + wr * 64 + m * 16 + fr;
;                 const bf16_t* brow = X1B + (size_t)(row < SEQ ? row + 2 : row + (X1B_PROMPT_ROWS - SEQ)) * DM + col0;
; #pragma unroll
;                 for (int bj = 0; bj < 2; ++bj)
; #pragma unroll
;                     for (int n = 0; n < 2; ++n) xb[m][bj][n] = *(const u32x2*)(brow + bj * 128 + n * 16);
;             }
;             asm volatile("" ::: "memory");
; #pragma unroll
;             for (int m = 0; m < 4; ++m) {
;                 const int row = u.pm * 256 + ai * 128 + wr * 64 + m * 16 + fr;
;                 float* orow = out + (size_t)row * DM + col0;
; #pragma unroll
;                 for (int bj = 0; bj < 2; ++bj)
; #pragma unroll
;                     for (int n = 0; n < 2; ++n) { const u32x2 b = xb[m][bj][n];
;                         const f32x4 xr = {__uint_as_float(b.x << 16), __uint_as_float(b.x & 0xffff0000u), __uint_as_float(b.y << 16), __uint_as_float(b.y & 0xffff0000u)};
;                         *(f32x4*)(orow + bj * 128 + n * 16) = xr + acc[ai][bj][m][n]; }
.LBB0_794:
	v_lshl_add_u32 v132, s21, 8, v164
	v_lshl_or_b32 v128, s30, 8, v166
	s_cmp_lt_i32 s21, 64
	s_cselect_b32 s43, 1, 64
	s_lshl_b32 s43, s43, 12
	s_add_u32 s16, s56, s43
	s_addc_u32 s17, s57, 0
	v_lshlrev_b32_e32 v129, 11, v132
	v_lshlrev_b32_e32 v133, 12, v132
	v_lshl_add_u32 v129, v128, 1, v129
	v_lshl_add_u32 v133, v128, 2, v133
	v_and_b32_e32 v128, 16, v226
	v_lshrrev_b32_e32 v132, 1, v128
	v_add3_u32 v129, v129, v128, v132
	global_load_dwordx4 v[136:139], v129, s[16:17]
	global_load_dwordx4 v[140:143], v129, s[16:17] offset:256
	s_add_u32 s18, s16, 0x8000
	s_addc_u32 s19, s17, 0
	global_load_dwordx4 v[144:147], v129, s[18:19]
	global_load_dwordx4 v[148:151], v129, s[18:19] offset:256
	s_add_u32 s18, s16, 0x10000
	s_addc_u32 s19, s17, 0
	global_load_dwordx4 v[152:155], v129, s[18:19]
	global_load_dwordx4 v[156:159], v129, s[18:19] offset:256
	s_add_u32 s18, s16, 0x18000
	s_addc_u32 s19, s17, 0
	global_load_dwordx4 v[160:163], v129, s[18:19]
	global_load_dwordx4 v[182:185], v129, s[18:19] offset:256
	s_add_u32 s18, s16, 0x40000
	s_addc_u32 s19, s17, 0
	global_load_dwordx4 v[186:189], v129, s[18:19]
	global_load_dwordx4 v[190:193], v129, s[18:19] offset:256
	s_add_u32 s18, s16, 0x48000
	s_addc_u32 s19, s17, 0
	global_load_dwordx4 v[194:197], v129, s[18:19]
	global_load_dwordx4 v[198:201], v129, s[18:19] offset:256
	s_add_u32 s18, s16, 0x50000
	s_addc_u32 s19, s17, 0
	global_load_dwordx4 v[202:205], v129, s[18:19]
	global_load_dwordx4 v[206:209], v129, s[18:19] offset:256
	s_add_u32 s18, s16, 0x58000
	s_addc_u32 s19, s17, 0
	global_load_dwordx4 v[210:213], v129, s[18:19]
	global_load_dwordx4 v[214:217], v129, s[18:19] offset:256
	s_waitcnt vmcnt(14)
	v_permlane16_swap_b32_e32 v136, v138
	v_permlane16_swap_b32_e32 v137, v139
	v_permlane16_swap_b32_e32 v140, v142
	v_permlane16_swap_b32_e32 v141, v143
	v_lshlrev_b32_e32 v130, 16, v136
	v_and_b32_e32 v131, 0xffff0000, v136
	v_lshlrev_b32_e32 v134, 16, v137
	v_and_b32_e32 v135, 0xffff0000, v137
	v_pk_add_f32 v[124:125], v[124:125], v[130:131]
	v_pk_add_f32 v[126:127], v[126:127], v[134:135]
	v_lshlrev_b32_e32 v130, 16, v138
	v_and_b32_e32 v131, 0xffff0000, v138
	v_lshlrev_b32_e32 v134, 16, v139
	v_and_b32_e32 v135, 0xffff0000, v139
	v_pk_add_f32 v[120:121], v[120:121], v[130:131]
	v_pk_add_f32 v[122:123], v[122:123], v[134:135]
	v_lshlrev_b32_e32 v130, 16, v140
	v_and_b32_e32 v131, 0xffff0000, v140
	v_lshlrev_b32_e32 v134, 16, v141
	v_and_b32_e32 v135, 0xffff0000, v141
	v_pk_add_f32 v[116:117], v[116:117], v[130:131]
	v_pk_add_f32 v[118:119], v[118:119], v[134:135]
	v_lshlrev_b32_e32 v130, 16, v142
	v_and_b32_e32 v131, 0xffff0000, v142
	v_lshlrev_b32_e32 v134, 16, v143
	v_and_b32_e32 v135, 0xffff0000, v143
	v_pk_add_f32 v[112:113], v[112:113], v[130:131]
	v_pk_add_f32 v[114:115], v[114:115], v[134:135]
	global_store_dwordx4 v133, v[124:127], s[6:7]
	global_store_dwordx4 v133, v[120:123], s[6:7] offset:64
	global_store_dwordx4 v133, v[116:119], s[6:7] offset:512
	global_store_dwordx4 v133, v[112:115], s[6:7] offset:576
	s_waitcnt vmcnt(16)
	v_permlane16_swap_b32_e32 v144, v146
	v_permlane16_swap_b32_e32 v145, v147
	v_permlane16_swap_b32_e32 v148, v150
	v_permlane16_swap_b32_e32 v149, v151
	v_lshlrev_b32_e32 v130, 16, v144
	v_and_b32_e32 v131, 0xffff0000, v144
	v_lshlrev_b32_e32 v134, 16, v145
	v_and_b32_e32 v135, 0xffff0000, v145
	v_pk_add_f32 v[108:109], v[108:109], v[130:131]
	v_pk_add_f32 v[110:111], v[110:111], v[134:135]
	v_lshlrev_b32_e32 v130, 16, v146
	v_and_b32_e32 v131, 0xffff0000, v146
	v_lshlrev_b32_e32 v134, 16, v147
	v_and_b32_e32 v135, 0xffff0000, v147
	v_pk_add_f32 v[104:105], v[104:105], v[130:131]
	v_pk_add_f32 v[106:107], v[106:107], v[134:135]
	v_lshlrev_b32_e32 v130, 16, v148
	v_and_b32_e32 v131, 0xffff0000, v148
	v_lshlrev_b32_e32 v134, 16, v149
	v_and_b32_e32 v135, 0xffff0000, v149
	v_pk_add_f32 v[100:101], v[100:101], v[130:131]
	v_pk_add_f32 v[102:103], v[102:103], v[134:135]
	v_lshlrev_b32_e32 v130, 16, v150
	v_and_b32_e32 v131, 0xffff0000, v150
	v_lshlrev_b32_e32 v134, 16, v151
	v_and_b32_e32 v135, 0xffff0000, v151
	v_pk_add_f32 v[92:93], v[92:93], v[130:131]
	v_pk_add_f32 v[94:95], v[94:95], v[134:135]
	s_add_u32 s36, s6, 0x10000
	s_addc_u32 s37, s7, 0
	global_store_dwordx4 v133, v[108:111], s[36:37]
	global_store_dwordx4 v133, v[104:107], s[36:37] offset:64
	global_store_dwordx4 v133, v[100:103], s[36:37] offset:512
	global_store_dwordx4 v133, v[92:95], s[36:37] offset:576
	s_waitcnt vmcnt(18)
	v_permlane16_swap_b32_e32 v152, v154
	v_permlane16_swap_b32_e32 v153, v155
	v_permlane16_swap_b32_e32 v156, v158
	v_permlane16_swap_b32_e32 v157, v159
	v_lshlrev_b32_e32 v130, 16, v152
	v_and_b32_e32 v131, 0xffff0000, v152
	v_lshlrev_b32_e32 v134, 16, v153
	v_and_b32_e32 v135, 0xffff0000, v153
	v_pk_add_f32 v[96:97], v[96:97], v[130:131]
	v_pk_add_f32 v[98:99], v[98:99], v[134:135]
	v_lshlrev_b32_e32 v130, 16, v154
	v_and_b32_e32 v131, 0xffff0000, v154
	v_lshlrev_b32_e32 v134, 16, v155
	v_and_b32_e32 v135, 0xffff0000, v155
	v_pk_add_f32 v[88:89], v[88:89], v[130:131]
	v_pk_add_f32 v[90:91], v[90:91], v[134:135]
	v_lshlrev_b32_e32 v130, 16, v156
	v_and_b32_e32 v131, 0xffff0000, v156
	v_lshlrev_b32_e32 v134, 16, v157
	v_and_b32_e32 v135, 0xffff0000, v157
	v_pk_add_f32 v[84:85], v[84:85], v[130:131]
	v_pk_add_f32 v[86:87], v[86:87], v[134:135]
	v_lshlrev_b32_e32 v130, 16, v158
	v_and_b32_e32 v131, 0xffff0000, v158
	v_lshlrev_b32_e32 v134, 16, v159
	v_and_b32_e32 v135, 0xffff0000, v159
	v_pk_add_f32 v[76:77], v[76:77], v[130:131]
	v_pk_add_f32 v[78:79], v[78:79], v[134:135]
	s_add_u32 s36, s6, 0x20000
	s_addc_u32 s37, s7, 0
	global_store_dwordx4 v133, v[96:99], s[36:37]
	global_store_dwordx4 v133, v[88:91], s[36:37] offset:64
	global_store_dwordx4 v133, v[84:87], s[36:37] offset:512
	global_store_dwordx4 v133, v[76:79], s[36:37] offset:576
	s_waitcnt vmcnt(20)
;     DI void operator()(const AccT& acc, const Unit& u, int wr, int wc, int fr, int fq, LAS unsigned char*) const {
;     ...
;             for (int m = 0; m < 4; ++m) {
;                 const int row = u.pm * 256 + ai * 128 + wr * 64 + m * 16 + fr;
;                 float* orow = out + (size_t)row * DM + col0;
; #pragma unroll
;                 for (int bj = 0; bj < 2; ++bj)
; #pragma unroll
;                     for (int n = 0; n < 2; ++n) { const u32x2 b = xb[m][bj][n];
;                         const f32x4 xr = {__uint_as_float(b.x << 16), __uint_as_float(b.x & 0xffff0000u), __uint_as_float(b.y << 16), __uint_as_float(b.y & 0xffff0000u)};
;                         *(f32x4*)(orow + bj * 128 + n * 16) = xr + acc[ai][bj][m][n]; }
	v_permlane16_swap_b32_e32 v160, v162
	v_permlane16_swap_b32_e32 v161, v163
	v_permlane16_swap_b32_e32 v182, v184
	v_permlane16_swap_b32_e32 v183, v185
	v_lshlrev_b32_e32 v130, 16, v160
	v_and_b32_e32 v131, 0xffff0000, v160
	v_lshlrev_b32_e32 v134, 16, v161
	v_and_b32_e32 v135, 0xffff0000, v161
	v_pk_add_f32 v[80:81], v[80:81], v[130:131]
	v_pk_add_f32 v[82:83], v[82:83], v[134:135]
	v_lshlrev_b32_e32 v130, 16, v162
	v_and_b32_e32 v131, 0xffff0000, v162
	v_lshlrev_b32_e32 v134, 16, v163
	v_and_b32_e32 v135, 0xffff0000, v163
	v_pk_add_f32 v[72:73], v[72:73], v[130:131]
	v_pk_add_f32 v[74:75], v[74:75], v[134:135]
	v_lshlrev_b32_e32 v130, 16, v182
	v_and_b32_e32 v131, 0xffff0000, v182
	v_lshlrev_b32_e32 v134, 16, v183
	v_and_b32_e32 v135, 0xffff0000, v183
	v_pk_add_f32 v[68:69], v[68:69], v[130:131]
	v_pk_add_f32 v[70:71], v[70:71], v[134:135]
	v_lshlrev_b32_e32 v130, 16, v184
	v_and_b32_e32 v131, 0xffff0000, v184
	v_lshlrev_b32_e32 v134, 16, v185
	v_and_b32_e32 v135, 0xffff0000, v185
	v_pk_add_f32 v[64:65], v[64:65], v[130:131]
	v_pk_add_f32 v[66:67], v[66:67], v[134:135]
	s_add_u32 s36, s6, 0x30000
	s_addc_u32 s37, s7, 0
	global_store_dwordx4 v133, v[80:83], s[36:37]
	global_store_dwordx4 v133, v[72:75], s[36:37] offset:64
	global_store_dwordx4 v133, v[68:71], s[36:37] offset:512
	global_store_dwordx4 v133, v[64:67], s[36:37] offset:576
	s_waitcnt vmcnt(22)
	v_permlane16_swap_b32_e32 v186, v188
	v_permlane16_swap_b32_e32 v187, v189
	v_permlane16_swap_b32_e32 v190, v192
	v_permlane16_swap_b32_e32 v191, v193
	v_lshlrev_b32_e32 v130, 16, v186
	v_and_b32_e32 v131, 0xffff0000, v186
	v_lshlrev_b32_e32 v134, 16, v187
	v_and_b32_e32 v135, 0xffff0000, v187
	v_pk_add_f32 v[60:61], v[60:61], v[130:131]
	v_pk_add_f32 v[62:63], v[62:63], v[134:135]
	v_lshlrev_b32_e32 v130, 16, v188
	v_and_b32_e32 v131, 0xffff0000, v188
	v_lshlrev_b32_e32 v134, 16, v189
	v_and_b32_e32 v135, 0xffff0000, v189
	v_pk_add_f32 v[56:57], v[56:57], v[130:131]
	v_pk_add_f32 v[58:59], v[58:59], v[134:135]
	v_lshlrev_b32_e32 v130, 16, v190
	v_and_b32_e32 v131, 0xffff0000, v190
	v_lshlrev_b32_e32 v134, 16, v191
	v_and_b32_e32 v135, 0xffff0000, v191
	v_pk_add_f32 v[52:53], v[52:53], v[130:131]
	v_pk_add_f32 v[54:55], v[54:55], v[134:135]
	v_lshlrev_b32_e32 v130, 16, v192
	v_and_b32_e32 v131, 0xffff0000, v192
	v_lshlrev_b32_e32 v134, 16, v193
	v_and_b32_e32 v135, 0xffff0000, v193
	v_pk_add_f32 v[44:45], v[44:45], v[130:131]
	v_pk_add_f32 v[46:47], v[46:47], v[134:135]
	s_add_u32 s36, s6, 0x80000
	s_addc_u32 s37, s7, 0
	global_store_dwordx4 v133, v[60:63], s[36:37]
	global_store_dwordx4 v133, v[56:59], s[36:37] offset:64
	global_store_dwordx4 v133, v[52:55], s[36:37] offset:512
	global_store_dwordx4 v133, v[44:47], s[36:37] offset:576
	s_waitcnt vmcnt(24)
	v_permlane16_swap_b32_e32 v194, v196
	v_permlane16_swap_b32_e32 v195, v197
	v_permlane16_swap_b32_e32 v198, v200
	v_permlane16_swap_b32_e32 v199, v201
	v_lshlrev_b32_e32 v130, 16, v194
	v_and_b32_e32 v131, 0xffff0000, v194
	v_lshlrev_b32_e32 v134, 16, v195
	v_and_b32_e32 v135, 0xffff0000, v195
	v_pk_add_f32 v[48:49], v[48:49], v[130:131]
	v_pk_add_f32 v[50:51], v[50:51], v[134:135]
	v_lshlrev_b32_e32 v130, 16, v196
	v_and_b32_e32 v131, 0xffff0000, v196
	v_lshlrev_b32_e32 v134, 16, v197
	v_and_b32_e32 v135, 0xffff0000, v197
	v_pk_add_f32 v[40:41], v[40:41], v[130:131]
	v_pk_add_f32 v[42:43], v[42:43], v[134:135]
	v_lshlrev_b32_e32 v130, 16, v198
	v_and_b32_e32 v131, 0xffff0000, v198
	v_lshlrev_b32_e32 v134, 16, v199
	v_and_b32_e32 v135, 0xffff0000, v199
	v_pk_add_f32 v[36:37], v[36:37], v[130:131]
	v_pk_add_f32 v[38:39], v[38:39], v[134:135]
	v_lshlrev_b32_e32 v130, 16, v200
	v_and_b32_e32 v131, 0xffff0000, v200
	v_lshlrev_b32_e32 v134, 16, v201
	v_and_b32_e32 v135, 0xffff0000, v201
	v_pk_add_f32 v[28:29], v[28:29], v[130:131]
	v_pk_add_f32 v[30:31], v[30:31], v[134:135]
	s_add_u32 s36, s6, 0x90000
	s_addc_u32 s37, s7, 0
	global_store_dwordx4 v133, v[48:51], s[36:37]
	global_store_dwordx4 v133, v[40:43], s[36:37] offset:64
	global_store_dwordx4 v133, v[36:39], s[36:37] offset:512
	global_store_dwordx4 v133, v[28:31], s[36:37] offset:576
	s_waitcnt vmcnt(26)
	v_permlane16_swap_b32_e32 v202, v204
	v_permlane16_swap_b32_e32 v203, v205
	v_permlane16_swap_b32_e32 v206, v208
	v_permlane16_swap_b32_e32 v207, v209
	v_lshlrev_b32_e32 v130, 16, v202
	v_and_b32_e32 v131, 0xffff0000, v202
	v_lshlrev_b32_e32 v134, 16, v203
	v_and_b32_e32 v135, 0xffff0000, v203
	v_pk_add_f32 v[32:33], v[32:33], v[130:131]
	v_pk_add_f32 v[34:35], v[34:35], v[134:135]
	v_lshlrev_b32_e32 v130, 16, v204
	v_and_b32_e32 v131, 0xffff0000, v204
	v_lshlrev_b32_e32 v134, 16, v205
	v_and_b32_e32 v135, 0xffff0000, v205
	v_pk_add_f32 v[24:25], v[24:25], v[130:131]
	v_pk_add_f32 v[26:27], v[26:27], v[134:135]
	v_lshlrev_b32_e32 v130, 16, v206
	v_and_b32_e32 v131, 0xffff0000, v206
	v_lshlrev_b32_e32 v134, 16, v207
	v_and_b32_e32 v135, 0xffff0000, v207
	v_pk_add_f32 v[20:21], v[20:21], v[130:131]
	v_pk_add_f32 v[22:23], v[22:23], v[134:135]
	v_lshlrev_b32_e32 v130, 16, v208
	v_and_b32_e32 v131, 0xffff0000, v208
	v_lshlrev_b32_e32 v134, 16, v209
	v_and_b32_e32 v135, 0xffff0000, v209
	v_pk_add_f32 v[12:13], v[12:13], v[130:131]
	v_pk_add_f32 v[14:15], v[14:15], v[134:135]
	s_add_u32 s36, s6, 0xa0000
	s_addc_u32 s37, s7, 0
	global_store_dwordx4 v133, v[32:35], s[36:37]
	global_store_dwordx4 v133, v[24:27], s[36:37] offset:64
	global_store_dwordx4 v133, v[20:23], s[36:37] offset:512
	global_store_dwordx4 v133, v[12:15], s[36:37] offset:576
	s_waitcnt vmcnt(28)
	v_permlane16_swap_b32_e32 v210, v212
	v_permlane16_swap_b32_e32 v211, v213
	v_permlane16_swap_b32_e32 v214, v216
	v_permlane16_swap_b32_e32 v215, v217
	v_lshlrev_b32_e32 v130, 16, v210
	v_and_b32_e32 v131, 0xffff0000, v210
	v_lshlrev_b32_e32 v134, 16, v211
	v_and_b32_e32 v135, 0xffff0000, v211
	v_pk_add_f32 v[16:17], v[16:17], v[130:131]
	v_pk_add_f32 v[18:19], v[18:19], v[134:135]
	v_lshlrev_b32_e32 v130, 16, v212
	v_and_b32_e32 v131, 0xffff0000, v212
	v_lshlrev_b32_e32 v134, 16, v213
	v_and_b32_e32 v135, 0xffff0000, v213
	v_pk_add_f32 v[8:9], v[8:9], v[130:131]
	v_pk_add_f32 v[10:11], v[10:11], v[134:135]
	v_lshlrev_b32_e32 v130, 16, v214
	v_and_b32_e32 v131, 0xffff0000, v214
	v_lshlrev_b32_e32 v134, 16, v215
	v_and_b32_e32 v135, 0xffff0000, v215
	v_pk_add_f32 v[4:5], v[4:5], v[130:131]
	v_pk_add_f32 v[6:7], v[6:7], v[134:135]
	v_lshlrev_b32_e32 v130, 16, v216
	v_and_b32_e32 v131, 0xffff0000, v216
	v_lshlrev_b32_e32 v134, 16, v217
	v_and_b32_e32 v135, 0xffff0000, v217
	v_pk_add_f32 v[0:1], v[0:1], v[130:131]
	v_pk_add_f32 v[2:3], v[2:3], v[134:135]
	s_add_u32 s36, s6, 0xb0000
	s_addc_u32 s37, s7, 0
	global_store_dwordx4 v133, v[16:19], s[36:37]
	global_store_dwordx4 v133, v[8:11], s[36:37] offset:64
	global_store_dwordx4 v133, v[4:7], s[36:37] offset:512
	global_store_dwordx4 v133, v[0:3], s[36:37] offset:576
	s_mov_b64 s[0:1], -1
	s_cmp_eq_u32 s33, s29
	s_cbranch_scc1 .LBB0_787
; #define PG8_BAR __builtin_amdgcn_s_barrier()
; template <class Epi, class Sched, bool ALIGN_EPI>
; DI void gemm_phase(LAS unsigned char* lds, const Gemm g, const Sched& S, const Epi& E) {
;     ...
;         cur = nxt; cA = nA; cB = nB; ++ui;
;         if constexpr (ALIGN_EPI) { if (wr == 1) PG8_BAR; }
	s_and_b64 s[0:1], s[14:15], exec
	s_cselect_b32 s30, s22, s30
	s_cselect_b32 s21, s34, s21
	s_andn2_b64 vcc, exec, s[8:9]
	s_cbranch_vccnz .LBB0_786
	s_barrier
	s_branch .LBB0_786
